# out-projection K-loop group-norm rescale hook: its 16 per-row gss loads issued up front (one wait instead of 16 serialized round trips, twice per tile)
# speedup vs baseline: 1.0132x; 1.0132x over previous
;     __device__ __forceinline__ void khook(f32x4 (&acc)[2][2][4][2], const Unit& u, int t, int wr, int fr) const {
;         const int row0 = u.pm * BM + wr * 64 + fr;
;         const float* s0 = gss + (t == 4 ? 0 : 32768); const float w0 = t == 4 ? (1.0f / 256.0f) : (1.0f / 384.0f);
; #pragma unroll
;         for (int ai = 0; ai < 2; ++ai)
; #pragma unroll
;             for (int m = 0; m < 4; ++m) { const int row = row0 + ai * HALF + m * 16;
;                 const float ratio = rsqrtf(s0[row] * w0 + 1e-6f) * __builtin_sqrtf(s0[32768 + row] * (1.0f / 384.0f) + 1e-6f);
; #pragma unroll
;                 for (int bj = 0; bj < 2; ++bj)
; #pragma unroll
;                     for (int n = 0; n < 2; ++n) acc[ai][bj][m][n] *= ratio; }
;     }
.LBB0_800:
	s_cmpk_eq_i32 s62, 0x200
	s_cselect_b64 vcc, -1, 0
	s_and_b64 s[0:1], vcc, exec
	s_cselect_b32 s34, 0, 0x20000
	v_lshl_add_u64 v[136:137], v[188:189], 0, s[34:35]
	global_load_dword v130, v[136:137], off
	global_load_dword v191, v[136:137], off offset:64
	global_load_dword v192, v[136:137], off offset:128
	global_load_dword v193, v[136:137], off offset:192
	global_load_dword v194, v[136:137], off offset:512
	global_load_dword v195, v[136:137], off offset:576
	global_load_dword v196, v[136:137], off offset:640
	global_load_dword v197, v[136:137], off offset:704
	s_mov_b32 s98, 0x20000
	s_mov_b32 s99, 0
	v_lshl_add_u64 v[200:201], v[136:137], 0, s[98:99]
	global_load_dword v202, v[200:201], off
	global_load_dword v203, v[200:201], off offset:64
	global_load_dword v204, v[200:201], off offset:128
	global_load_dword v205, v[200:201], off offset:192
	global_load_dword v206, v[200:201], off offset:512
	global_load_dword v207, v[200:201], off offset:576
	global_load_dword v208, v[200:201], off offset:640
	global_load_dword v209, v[200:201], off offset:704
	v_cndmask_b32_e32 v128, v235, v236, vcc
	s_mov_b32 s0, 0x20000
	s_waitcnt vmcnt(0)
	v_fmaak_f32 v130, v128, v130, 0x358637bd
	v_cmp_gt_f32_e32 vcc, s36, v130
	v_mul_f32_e32 v131, 0x4b800000, v130
	s_nop 0
	v_cndmask_b32_e32 v130, v130, v131, vcc
	v_rsq_f32_e32 v130, v130
	s_nop 0
	v_mul_f32_e32 v131, 0x45800000, v130
	v_cndmask_b32_e32 v138, v130, v131, vcc
	v_add_co_u32_e32 v130, vcc, s0, v136
	s_nop 1
	v_addc_co_u32_e32 v131, vcc, 0, v137, vcc
	v_fmamk_f32 v139, v202, 0x3b2aaaab, v227
	v_cmp_gt_f32_e32 vcc, s88, v139
	v_mul_f32_e32 v140, 0x4f800000, v139
	s_nop 0
	v_cndmask_b32_e32 v139, v139, v140, vcc
	v_sqrt_f32_e32 v140, v139
	s_nop 0
	v_add_u32_e32 v141, -1, v140
	v_fma_f32 v142, -v141, v140, v139
	v_cmp_ge_f32_e64 s[0:1], 0, v142
	v_add_u32_e32 v142, 1, v140
	s_nop 0
	v_cndmask_b32_e64 v141, v140, v141, s[0:1]
	v_fma_f32 v140, -v142, v140, v139
	v_cmp_lt_f32_e64 s[0:1], 0, v140
	s_nop 1
	v_cndmask_b32_e64 v140, v141, v142, s[0:1]
	v_mul_f32_e32 v141, 0x37800000, v140
	v_cndmask_b32_e32 v140, v140, v141, vcc
	v_cmp_class_f32_e32 vcc, v139, v229
	s_nop 1
	v_cndmask_b32_e32 v139, v140, v139, vcc
	v_mul_f32_e32 v138, v139, v138
	v_pk_mul_f32 v[126:127], v[126:127], v[138:139] op_sel_hi:[1,0]
	v_pk_mul_f32 v[124:125], v[124:125], v[138:139] op_sel_hi:[1,0]
	v_pk_mul_f32 v[122:123], v[122:123], v[138:139] op_sel_hi:[1,0]
	v_pk_mul_f32 v[120:121], v[120:121], v[138:139] op_sel_hi:[1,0]
	v_pk_mul_f32 v[62:63], v[62:63], v[138:139] op_sel_hi:[1,0]
	v_pk_mul_f32 v[60:61], v[60:61], v[138:139] op_sel_hi:[1,0]
	v_pk_mul_f32 v[58:59], v[58:59], v[138:139] op_sel_hi:[1,0]
	v_pk_mul_f32 v[56:57], v[56:57], v[138:139] op_sel_hi:[1,0]
	v_fmaak_f32 v138, v128, v191, 0x358637bd
	v_cmp_gt_f32_e32 vcc, s36, v138
	v_mul_f32_e32 v139, 0x4b800000, v138
	s_nop 0
	v_cndmask_b32_e32 v138, v138, v139, vcc
	v_rsq_f32_e32 v138, v138
	s_nop 0
	v_mul_f32_e32 v139, 0x45800000, v138
	v_cndmask_b32_e32 v138, v138, v139, vcc
	v_fmamk_f32 v139, v203, 0x3b2aaaab, v227
	v_cmp_gt_f32_e32 vcc, s88, v139
	v_mul_f32_e32 v140, 0x4f800000, v139
	s_nop 0
	v_cndmask_b32_e32 v139, v139, v140, vcc
	v_sqrt_f32_e32 v140, v139
	s_nop 0
	v_add_u32_e32 v141, -1, v140
	v_fma_f32 v142, -v141, v140, v139
	v_cmp_ge_f32_e64 s[0:1], 0, v142
	v_add_u32_e32 v142, 1, v140
	s_nop 0
	v_cndmask_b32_e64 v141, v140, v141, s[0:1]
	v_fma_f32 v140, -v142, v140, v139
	v_cmp_lt_f32_e64 s[0:1], 0, v140
	s_nop 1
	v_cndmask_b32_e64 v140, v141, v142, s[0:1]
	v_mul_f32_e32 v141, 0x37800000, v140
	v_cndmask_b32_e32 v140, v140, v141, vcc
	v_cmp_class_f32_e32 vcc, v139, v229
	s_nop 1
	v_cndmask_b32_e32 v139, v140, v139, vcc
	v_mul_f32_e32 v138, v139, v138
	v_pk_mul_f32 v[118:119], v[118:119], v[138:139] op_sel_hi:[1,0]
	v_pk_mul_f32 v[116:117], v[116:117], v[138:139] op_sel_hi:[1,0]
	v_pk_mul_f32 v[114:115], v[114:115], v[138:139] op_sel_hi:[1,0]
	v_pk_mul_f32 v[112:113], v[112:113], v[138:139] op_sel_hi:[1,0]
	v_pk_mul_f32 v[54:55], v[54:55], v[138:139] op_sel_hi:[1,0]
	v_pk_mul_f32 v[52:53], v[52:53], v[138:139] op_sel_hi:[1,0]
	v_pk_mul_f32 v[50:51], v[50:51], v[138:139] op_sel_hi:[1,0]
	v_pk_mul_f32 v[48:49], v[48:49], v[138:139] op_sel_hi:[1,0]
	v_fmaak_f32 v138, v128, v192, 0x358637bd
	v_cmp_gt_f32_e32 vcc, s36, v138
	v_mul_f32_e32 v139, 0x4b800000, v138
	s_nop 0
	v_cndmask_b32_e32 v138, v138, v139, vcc
	v_rsq_f32_e32 v138, v138
	s_nop 0
	v_mul_f32_e32 v139, 0x45800000, v138
	v_cndmask_b32_e32 v138, v138, v139, vcc
	v_fmamk_f32 v139, v204, 0x3b2aaaab, v227
	v_cmp_gt_f32_e32 vcc, s88, v139
	v_mul_f32_e32 v140, 0x4f800000, v139
	s_nop 0
	v_cndmask_b32_e32 v139, v139, v140, vcc
	v_sqrt_f32_e32 v140, v139
	s_nop 0
	v_add_u32_e32 v141, -1, v140
	v_fma_f32 v142, -v141, v140, v139
	v_cmp_ge_f32_e64 s[0:1], 0, v142
	v_add_u32_e32 v142, 1, v140
	s_nop 0
	v_cndmask_b32_e64 v141, v140, v141, s[0:1]
	v_fma_f32 v140, -v142, v140, v139
	v_cmp_lt_f32_e64 s[0:1], 0, v140
	s_nop 1
	v_cndmask_b32_e64 v140, v141, v142, s[0:1]
	v_mul_f32_e32 v141, 0x37800000, v140
	v_cndmask_b32_e32 v140, v140, v141, vcc
	v_cmp_class_f32_e32 vcc, v139, v229
	s_nop 1
	v_cndmask_b32_e32 v139, v140, v139, vcc
	v_mul_f32_e32 v138, v139, v138
	v_pk_mul_f32 v[110:111], v[110:111], v[138:139] op_sel_hi:[1,0]
	v_pk_mul_f32 v[108:109], v[108:109], v[138:139] op_sel_hi:[1,0]
	v_pk_mul_f32 v[106:107], v[106:107], v[138:139] op_sel_hi:[1,0]
	v_pk_mul_f32 v[104:105], v[104:105], v[138:139] op_sel_hi:[1,0]
	v_pk_mul_f32 v[46:47], v[46:47], v[138:139] op_sel_hi:[1,0]
	v_pk_mul_f32 v[44:45], v[44:45], v[138:139] op_sel_hi:[1,0]
	v_pk_mul_f32 v[42:43], v[42:43], v[138:139] op_sel_hi:[1,0]
;     __device__ __forceinline__ void khook(f32x4 (&acc)[2][2][4][2], const Unit& u, int t, int wr, int fr) const {
;     ...
;             for (int m = 0; m < 4; ++m) { const int row = row0 + ai * HALF + m * 16;
;                 const float ratio = rsqrtf(s0[row] * w0 + 1e-6f) * __builtin_sqrtf(s0[32768 + row] * (1.0f / 384.0f) + 1e-6f);
; #pragma unroll
;                 for (int bj = 0; bj < 2; ++bj)
; #pragma unroll
;                     for (int n = 0; n < 2; ++n) acc[ai][bj][m][n] *= ratio; }
	v_pk_mul_f32 v[40:41], v[40:41], v[138:139] op_sel_hi:[1,0]
	v_fmaak_f32 v138, v128, v193, 0x358637bd
	v_cmp_gt_f32_e32 vcc, s36, v138
	v_mul_f32_e32 v139, 0x4b800000, v138
	s_nop 0
	v_cndmask_b32_e32 v138, v138, v139, vcc
	v_rsq_f32_e32 v138, v138
	s_nop 0
	v_mul_f32_e32 v139, 0x45800000, v138
	v_cndmask_b32_e32 v138, v138, v139, vcc
	v_fmamk_f32 v139, v205, 0x3b2aaaab, v227
	v_cmp_gt_f32_e32 vcc, s88, v139
	v_mul_f32_e32 v140, 0x4f800000, v139
	s_nop 0
	v_cndmask_b32_e32 v139, v139, v140, vcc
	v_sqrt_f32_e32 v140, v139
	s_nop 0
	v_add_u32_e32 v141, -1, v140
	v_fma_f32 v142, -v141, v140, v139
	v_cmp_ge_f32_e64 s[0:1], 0, v142
	v_add_u32_e32 v142, 1, v140
	s_nop 0
	v_cndmask_b32_e64 v141, v140, v141, s[0:1]
	v_fma_f32 v140, -v142, v140, v139
	v_cmp_lt_f32_e64 s[0:1], 0, v140
	s_nop 1
	v_cndmask_b32_e64 v140, v141, v142, s[0:1]
	v_mul_f32_e32 v141, 0x37800000, v140
	v_cndmask_b32_e32 v140, v140, v141, vcc
	v_cmp_class_f32_e32 vcc, v139, v229
	s_nop 1
	v_cndmask_b32_e32 v139, v140, v139, vcc
	v_mul_f32_e32 v138, v139, v138
	v_pk_mul_f32 v[102:103], v[102:103], v[138:139] op_sel_hi:[1,0]
	v_pk_mul_f32 v[100:101], v[100:101], v[138:139] op_sel_hi:[1,0]
	v_pk_mul_f32 v[98:99], v[98:99], v[138:139] op_sel_hi:[1,0]
	v_pk_mul_f32 v[96:97], v[96:97], v[138:139] op_sel_hi:[1,0]
	v_pk_mul_f32 v[38:39], v[38:39], v[138:139] op_sel_hi:[1,0]
	v_pk_mul_f32 v[36:37], v[36:37], v[138:139] op_sel_hi:[1,0]
	v_pk_mul_f32 v[34:35], v[34:35], v[138:139] op_sel_hi:[1,0]
	v_pk_mul_f32 v[32:33], v[32:33], v[138:139] op_sel_hi:[1,0]
	v_fmaak_f32 v138, v128, v194, 0x358637bd
	v_cmp_gt_f32_e32 vcc, s36, v138
	v_mul_f32_e32 v139, 0x4b800000, v138
	s_nop 0
	v_cndmask_b32_e32 v138, v138, v139, vcc
	v_rsq_f32_e32 v138, v138
	s_nop 0
	v_mul_f32_e32 v139, 0x45800000, v138
	v_cndmask_b32_e32 v138, v138, v139, vcc
	v_fmamk_f32 v139, v206, 0x3b2aaaab, v227
	v_cmp_gt_f32_e32 vcc, s88, v139
	v_mul_f32_e32 v140, 0x4f800000, v139
	s_nop 0
	v_cndmask_b32_e32 v139, v139, v140, vcc
	v_sqrt_f32_e32 v140, v139
	s_nop 0
	v_add_u32_e32 v141, -1, v140
	v_fma_f32 v142, -v141, v140, v139
	v_cmp_ge_f32_e64 s[0:1], 0, v142
	v_add_u32_e32 v142, 1, v140
	s_nop 0
	v_cndmask_b32_e64 v141, v140, v141, s[0:1]
	v_fma_f32 v140, -v142, v140, v139
	v_cmp_lt_f32_e64 s[0:1], 0, v140
	s_nop 1
	v_cndmask_b32_e64 v140, v141, v142, s[0:1]
	v_mul_f32_e32 v141, 0x37800000, v140
	v_cndmask_b32_e32 v140, v140, v141, vcc
	v_cmp_class_f32_e32 vcc, v139, v229
	s_nop 1
	v_cndmask_b32_e32 v139, v140, v139, vcc
	v_mul_f32_e32 v138, v139, v138
	v_pk_mul_f32 v[94:95], v[94:95], v[138:139] op_sel_hi:[1,0]
	v_pk_mul_f32 v[92:93], v[92:93], v[138:139] op_sel_hi:[1,0]
	v_pk_mul_f32 v[90:91], v[90:91], v[138:139] op_sel_hi:[1,0]
	v_pk_mul_f32 v[88:89], v[88:89], v[138:139] op_sel_hi:[1,0]
	v_pk_mul_f32 v[30:31], v[30:31], v[138:139] op_sel_hi:[1,0]
	v_pk_mul_f32 v[28:29], v[28:29], v[138:139] op_sel_hi:[1,0]
	v_pk_mul_f32 v[26:27], v[26:27], v[138:139] op_sel_hi:[1,0]
	v_pk_mul_f32 v[24:25], v[24:25], v[138:139] op_sel_hi:[1,0]
	v_fmaak_f32 v138, v128, v195, 0x358637bd
	v_cmp_gt_f32_e32 vcc, s36, v138
	v_mul_f32_e32 v139, 0x4b800000, v138
	s_nop 0
	v_cndmask_b32_e32 v138, v138, v139, vcc
	v_rsq_f32_e32 v138, v138
	s_nop 0
	v_mul_f32_e32 v139, 0x45800000, v138
	v_cndmask_b32_e32 v138, v138, v139, vcc
	v_fmamk_f32 v139, v207, 0x3b2aaaab, v227
	v_cmp_gt_f32_e32 vcc, s88, v139
	v_mul_f32_e32 v140, 0x4f800000, v139
	s_nop 0
	v_cndmask_b32_e32 v139, v139, v140, vcc
	v_sqrt_f32_e32 v140, v139
	s_nop 0
	v_add_u32_e32 v141, -1, v140
	v_fma_f32 v142, -v141, v140, v139
	v_cmp_ge_f32_e64 s[0:1], 0, v142
	v_add_u32_e32 v142, 1, v140
	s_nop 0
	v_cndmask_b32_e64 v141, v140, v141, s[0:1]
;     __device__ __forceinline__ void khook(f32x4 (&acc)[2][2][4][2], const Unit& u, int t, int wr, int fr) const {
;     ...
;             for (int m = 0; m < 4; ++m) { const int row = row0 + ai * HALF + m * 16;
;                 const float ratio = rsqrtf(s0[row] * w0 + 1e-6f) * __builtin_sqrtf(s0[32768 + row] * (1.0f / 384.0f) + 1e-6f);
; #pragma unroll
;                 for (int bj = 0; bj < 2; ++bj)
; #pragma unroll
;                     for (int n = 0; n < 2; ++n) acc[ai][bj][m][n] *= ratio; }
	v_fma_f32 v140, -v142, v140, v139
	v_cmp_lt_f32_e64 s[0:1], 0, v140
	s_nop 1
	v_cndmask_b32_e64 v140, v141, v142, s[0:1]
	v_mul_f32_e32 v141, 0x37800000, v140
	v_cndmask_b32_e32 v140, v140, v141, vcc
	v_cmp_class_f32_e32 vcc, v139, v229
	s_nop 1
	v_cndmask_b32_e32 v139, v140, v139, vcc
	v_mul_f32_e32 v138, v139, v138
	v_pk_mul_f32 v[86:87], v[86:87], v[138:139] op_sel_hi:[1,0]
	v_pk_mul_f32 v[84:85], v[84:85], v[138:139] op_sel_hi:[1,0]
	v_pk_mul_f32 v[82:83], v[82:83], v[138:139] op_sel_hi:[1,0]
	v_pk_mul_f32 v[80:81], v[80:81], v[138:139] op_sel_hi:[1,0]
	v_pk_mul_f32 v[22:23], v[22:23], v[138:139] op_sel_hi:[1,0]
	v_pk_mul_f32 v[20:21], v[20:21], v[138:139] op_sel_hi:[1,0]
	v_pk_mul_f32 v[18:19], v[18:19], v[138:139] op_sel_hi:[1,0]
	v_pk_mul_f32 v[16:17], v[16:17], v[138:139] op_sel_hi:[1,0]
	v_fmaak_f32 v138, v128, v196, 0x358637bd
	v_cmp_gt_f32_e32 vcc, s36, v138
	v_mul_f32_e32 v139, 0x4b800000, v138
	v_cndmask_b32_e32 v138, v138, v139, vcc
	v_rsq_f32_e32 v138, v138
	v_fmaak_f32 v128, v128, v197, 0x358637bd
	v_mul_f32_e32 v139, 0x45800000, v138
	v_cndmask_b32_e32 v138, v138, v139, vcc
	v_mul_f32_e32 v136, 0x4b800000, v128
	v_fmamk_f32 v139, v208, 0x3b2aaaab, v227
	v_cmp_gt_f32_e32 vcc, s88, v139
	v_mul_f32_e32 v140, 0x4f800000, v139
	v_fmamk_f32 v130, v209, 0x3b2aaaab, v227
	v_cndmask_b32_e32 v139, v139, v140, vcc
	v_sqrt_f32_e32 v140, v139
	v_mul_f32_e32 v131, 0x4f800000, v130
	v_add_u32_e32 v141, -1, v140
	v_fma_f32 v142, -v141, v140, v139
	v_cmp_ge_f32_e64 s[0:1], 0, v142
	v_add_u32_e32 v142, 1, v140
	s_nop 0
	v_cndmask_b32_e64 v141, v140, v141, s[0:1]
	v_fma_f32 v140, -v142, v140, v139
	v_cmp_lt_f32_e64 s[0:1], 0, v140
	s_nop 1
	v_cndmask_b32_e64 v140, v141, v142, s[0:1]
	v_mul_f32_e32 v141, 0x37800000, v140
	v_cndmask_b32_e32 v140, v140, v141, vcc
	v_cmp_class_f32_e32 vcc, v139, v229
	s_nop 1
	v_cndmask_b32_e32 v139, v140, v139, vcc
	v_cmp_gt_f32_e32 vcc, s36, v128
	v_mul_f32_e32 v138, v139, v138
	v_pk_mul_f32 v[78:79], v[78:79], v[138:139] op_sel_hi:[1,0]
	v_cndmask_b32_e32 v128, v128, v136, vcc
	v_rsq_f32_e32 v128, v128
	v_pk_mul_f32 v[76:77], v[76:77], v[138:139] op_sel_hi:[1,0]
	v_pk_mul_f32 v[74:75], v[74:75], v[138:139] op_sel_hi:[1,0]
	v_pk_mul_f32 v[72:73], v[72:73], v[138:139] op_sel_hi:[1,0]
	v_mul_f32_e32 v136, 0x45800000, v128
	v_cndmask_b32_e32 v128, v128, v136, vcc
	v_cmp_gt_f32_e32 vcc, s88, v130
	v_pk_mul_f32 v[14:15], v[14:15], v[138:139] op_sel_hi:[1,0]
	v_pk_mul_f32 v[12:13], v[12:13], v[138:139] op_sel_hi:[1,0]
	v_cndmask_b32_e32 v130, v130, v131, vcc
	v_sqrt_f32_e32 v131, v130
	v_pk_mul_f32 v[10:11], v[10:11], v[138:139] op_sel_hi:[1,0]
	v_pk_mul_f32 v[8:9], v[8:9], v[138:139] op_sel_hi:[1,0]
	v_add_u32_e32 v136, -1, v131
	v_fma_f32 v137, -v136, v131, v130
	v_cmp_ge_f32_e64 s[0:1], 0, v137
	v_add_u32_e32 v137, 1, v131
	s_nop 0
	v_cndmask_b32_e64 v136, v131, v136, s[0:1]
	v_fma_f32 v131, -v137, v131, v130
	v_cmp_lt_f32_e64 s[0:1], 0, v131
	s_nop 1
	v_cndmask_b32_e64 v131, v136, v137, s[0:1]
	v_mul_f32_e32 v136, 0x37800000, v131
	v_cndmask_b32_e32 v131, v131, v136, vcc
	v_cmp_class_f32_e32 vcc, v130, v229
	s_nop 1
	v_cndmask_b32_e32 v130, v131, v130, vcc
	v_mul_f32_e32 v128, v130, v128
	v_pk_mul_f32 v[70:71], v[70:71], v[128:129] op_sel_hi:[1,0]
	v_pk_mul_f32 v[68:69], v[68:69], v[128:129] op_sel_hi:[1,0]
	v_pk_mul_f32 v[66:67], v[66:67], v[128:129] op_sel_hi:[1,0]
	v_pk_mul_f32 v[64:65], v[64:65], v[128:129] op_sel_hi:[1,0]
	v_pk_mul_f32 v[6:7], v[6:7], v[128:129] op_sel_hi:[1,0]
	v_pk_mul_f32 v[4:5], v[4:5], v[128:129] op_sel_hi:[1,0]
	v_pk_mul_f32 v[2:3], v[2:3], v[128:129] op_sel_hi:[1,0]
	v_pk_mul_f32 v[0:1], v[0:1], v[128:129] op_sel_hi:[1,0]
